# hgrn stage 3: static s_setprio 2 on the four matrix-pipe waves so the context-unit wave sharing SIMD 0 does not slow wave 0's latent units
# speedup vs baseline: 1.0048x; 1.0048x over previous
.LBB0_587:
	v_readlane_b32 s0, v254, 14
	s_cmp_gt_i32 s0, 3
	s_cbranch_scc1 .LBB0_592
	s_setprio 2
	v_readlane_b32 s0, v252, 29
	v_readlane_b32 s1, v254, 14
	s_mul_i32 s0, s1, s0
	v_readlane_b32 s1, v252, 30
	s_add_i32 s6, s0, s1
	s_cmpk_gt_i32 s6, 0x3ff
	s_cbranch_scc1 .LBB0_592
	v_readlane_b32 s0, v254, 14
	s_lshl_b32 s0, s0, 15
	s_add_i32 s7, s0, 0
	s_lshl_b32 s8, s6, 4

.LBB0_592:
	s_setprio 0
	v_readlane_b32 s0, v252, 32
	v_readlane_b32 s1, v252, 33
	s_andn2_b64 vcc, exec, s[0:1]
	s_barrier
	s_cbranch_vccnz .LBB0_698
	v_readlane_b32 s0, v254, 8
	v_readlane_b32 s2, v254, 10
	v_readlane_b32 s3, v254, 11
	s_add_u32 s12, s2, 0x5600800
	s_addc_u32 s13, s3, 0
	s_add_u32 s14, s2, 0x5600b00
	s_addc_u32 s15, s3, 0
	v_readlane_b32 s16, v252, 31
	v_readlane_b32 s1, v254, 9
	s_branch .LBB0_595
